# SSD: waves 4-7 take row blocks 7..4 (logical wave id w^3 for w>=4) so each SIMD's two waves do 9 causal blocks instead of 6..12
# baseline (speedup 1.0000x reference)
.LBB0_1069:
	s_cmpk_gt_i32 s80, 0xff
	s_waitcnt vmcnt(0) lgkmcnt(0)
	s_barrier
	s_cbranch_scc1 .LBB0_1143
	v_lshlrev_b32_e32 v160, 3, v0
	s_add_i32 s0, 0, 0x1dc00
	v_add_u32_e32 v4, s0, v160
	s_add_i32 s0, 0, 0x22000
	s_add_i32 s1, 0, 0x15400
	v_lshl_add_u32 v161, v156, 2, s0
	s_movk_i32 s0, 0x440
	v_writelane_b32 v254, s1, 14
	v_mad_i32_i24 v202, v0, s0, 0
	s_add_u32 s0, s84, 0x100000
	v_writelane_b32 v254, s0, 15
	s_addc_u32 s0, s85, 0
	v_writelane_b32 v254, s0, 16
	s_and_b32 s9, s85, 0xffff
	s_mov_b32 s8, s84
	v_writelane_b32 v254, s84, 17
	v_and_b32_e32 v157, 15, v182
	v_lshrrev_b32_e32 v1, 4, v182
	v_bfe_u32 v3, v182, 8, 1
	v_mul_u32_u24_e32 v3, 12, v3
	v_xor_b32_e32 v1, v1, v3
	v_writelane_b32 v254, s85, 18
	v_writelane_b32 v254, s86, 19
	v_lshlrev_b32_e32 v2, 1, v137
	v_lshlrev_b32_e32 v163, 2, v0
	v_lshl_add_u32 v164, v0, 4, 0
	v_mul_u32_u24_e32 v7, 0x88, v1
	v_lshl_add_u32 v204, v0, 5, 0
	v_lshl_add_u32 v0, v157, 2, 0
	v_writelane_b32 v254, s87, 20
	v_add_u32_e32 v3, 0, v2
	v_and_b32_e32 v162, 48, v182
	v_lshlrev_b32_e32 v7, 1, v7
	v_add_u32_e32 v205, 0x22200, v0
	v_mbcnt_lo_u32_b32 v0, -1, 0
	v_writelane_b32 v254, s81, 21
	v_lshl_or_b32 v158, v1, 8, v2
	v_lshl_or_b32 v159, v1, 12, v2
	v_add_u32_e32 v5, 0, v162
	v_add_u32_e32 v6, v4, v160
	v_add_u32_e32 v165, v3, v7
	v_add3_u32 v166, s1, v2, v7
	s_movk_i32 s1, 0x110
	v_mul_u32_u24_e32 v2, 0x110, v1
	v_mul_u32_u24_e32 v169, 0x110, v157
	v_mov_b32_e32 v1, 0
	v_mbcnt_hi_u32_b32 v209, -1, v0
	v_bfrev_b32_e32 v0, 0.5
	v_writelane_b32 v254, s82, 22
	v_add_u32_e32 v167, 0xcc00, v165
	v_add_u32_e32 v168, 0x2200, v166
	v_or_b32_e32 v253, 1, v163
	v_or_b32_e32 v206, 2, v163
	v_or_b32_e32 v172, 3, v163
	v_or_b32_e32 v173, 16, v163
	v_or_b32_e32 v174, 17, v163
	v_or_b32_e32 v175, 18, v163
	v_or_b32_e32 v176, 19, v163
	v_or_b32_e32 v177, 32, v163
	v_or_b32_e32 v178, 33, v163
	v_or_b32_e32 v179, 34, v163
	v_or_b32_e32 v180, 35, v163
	v_or_b32_e32 v181, 48, v163
	v_or_b32_e32 v183, 49, v163
	v_or_b32_e32 v184, 50, v163
	v_or_b32_e32 v185, 51, v163
	v_or_b32_e32 v186, 64, v163
	v_or_b32_e32 v187, 0x41, v163
	v_or_b32_e32 v188, 0x42, v163
	v_or_b32_e32 v189, 0x43, v163
	v_or_b32_e32 v190, 0x50, v163
	v_or_b32_e32 v191, 0x51, v163
	v_or_b32_e32 v192, 0x52, v163
	v_or_b32_e32 v193, 0x53, v163
	v_or_b32_e32 v194, 0x60, v163
	v_or_b32_e32 v195, 0x61, v163
	v_or_b32_e32 v196, 0x62, v163
	v_or_b32_e32 v197, 0x63, v163
	v_or_b32_e32 v198, 0x70, v163
	v_or_b32_e32 v199, 0x71, v163
	v_or_b32_e32 v200, 0x72, v163
	v_or_b32_e32 v201, 0x73, v163
	s_mov_b32 s11, 0x20000
	s_brev_b32 s10, -2
	s_and_b32 s13, s13, 0xffff
	v_mad_u32_u24 v203, v157, s1, v4
	v_add_u32_e32 v207, v6, v169
	v_add_u32_e32 v208, v3, v2
	v_lshl_or_b32 v210, v209, 2, v0
	v_add_u32_e32 v211, v5, v169
	v_mov_b32_e32 v170, v1
	v_mov_b32_e32 v171, v1
	v_writelane_b32 v254, s83, 23
	s_branch .LBB0_1072

.LBB0_1072:
	s_ashr_i32 s0, s80, 31
	s_lshr_b32 s1, s0, 29
	s_lshr_b32 s0, s0, 30
	s_add_i32 s0, s80, s0
	s_bfe_u32 s14, s0, 0x10002
	s_lshr_b32 s0, s80, 31
	s_add_i32 s0, s80, s0
	s_bfe_u32 s3, s0, 0x10001
	s_and_b32 s0, s0, 0x3ffffffe
	s_add_i32 s1, s80, s1
	s_sub_i32 s0, s80, s0
	s_ashr_i32 s2, s1, 3
	v_readfirstlane_b32 s1, v182
	s_bitcmp1_b32 s1, 8
	s_cselect_b32 s88, 0xc0, 0
	s_xor_b32 s1, s1, s88
	s_lshl_b32 s4, s14, 3
	s_lshl_b32 s0, s0, 2
	s_add_i32 s0, s4, s0
	s_bfe_u32 s15, s1, 0x20006
	s_cmp_eq_u32 s3, 0
	s_cselect_b64 s[4:5], -1, 0
	s_and_b64 vcc, s[4:5], exec
	v_readlane_b32 s6, v254, 9
	v_readlane_b32 s7, v254, 11
	s_cselect_b32 s16, s6, s7
	v_readlane_b32 s6, v254, 8
	v_readlane_b32 s7, v254, 10
	s_cselect_b32 s17, s6, s7
	s_or_b32 s6, s15, s0
	s_ashr_i32 s7, s6, 31
	s_lshl_b64 s[6:7], s[6:7], 2
	s_add_u32 s6, s17, s6
	s_addc_u32 s7, s16, s7
	v_mov_b64_e32 v[2:3], s[6:7]
	flat_load_dword v0, v[2:3]
	s_mov_b64 s[6:7], -1
	s_cbranch_vccnz .LBB0_1074
	s_lshl_b32 s18, s2, 22
	s_add_i32 s16, s18, 0x4000000
	s_mov_b64 s[6:7], 0
